# attention loops: K-fragment LDS reads of QK^T software-pipelined (4-slot ring) plus waves 4-7 MFMA sections at s_setprio 2 so their P.V keeps the matrix pipe against the partner's denser QK^T burst; s
# speedup vs baseline: 1.0089x; 1.0089x over previous
; #define SBAR() __builtin_amdgcn_sched_barrier(0)
; #define PV_LOAD(S, DD) do { S[0] = tr_read<v_off8(DD, 0, 0)>(vb); S[1] = tr_read<v_off8(DD, 0, 1)>(vb); S[2] = tr_read<v_off8(DD, 1, 0)>(vb); S[3] = tr_read<v_off8(DD, 1, 1)>(vb); \
;     S[4] = tr_read<v_off8(DD, 2, 0)>(vb); S[5] = tr_read<v_off8(DD, 2, 1)>(vb); S[6] = tr_read<v_off8(DD, 3, 0)>(vb); S[7] = tr_read<v_off8(DD, 3, 1)>(vb); } while (0)
; #define PV_MMA(OD, S) do { OD = __builtin_amdgcn_mfma_f32_32x32x16_bf16(pa0, PV_PK(S[0], S[1]), OD, 0, 0, 0); OD = __builtin_amdgcn_mfma_f32_32x32x16_bf16(pa1, PV_PK(S[2], S[3]), OD, 0, 0, 0); \
;     OD = __builtin_amdgcn_mfma_f32_32x32x16_bf16(pa2, PV_PK(S[4], S[5]), OD, 0, 0, 0); OD = __builtin_amdgcn_mfma_f32_32x32x16_bf16(pa3, PV_PK(S[6], S[7]), OD, 0, 0, 0); } while (0)
; #define PV_W8() do { asm volatile("s_waitcnt lgkmcnt(8)" ::: "memory"); SBAR(); } while (0)
; #define PV_W0() do { asm volatile("s_waitcnt lgkmcnt(0)" ::: "memory"); SBAR(); } while (0)
; __device__ __forceinline__ void qkt(f32x16& p0, f32x16& p1, const char* Ks, const bf16x8* qr, int r32, int hi, const LAS float* tab, int rel0, int farmode) {
;   if (farmode != 0) { const float c = tab[farmode < 0 ? 0 : 384];
; #pragma unroll
;     for (int r = 0; r < 16; ++r) { p0[r] = c; p1[r] = c; }
; __device__ __forceinline__ void pv8(f32x16* o, int vb, bf16x8 pa0, bf16x8 pa1, bf16x8 pa2, bf16x8 pa3) {
;   s16x4 A[8], B[8];
;   PV_LOAD(A, 0);
;   PV_LOAD(B, 1); PV_W8(); PV_MMA(o[0], A); SBAR();
;   PV_LOAD(A, 2); PV_W8(); PV_MMA(o[1], B); SBAR();
;   PV_LOAD(B, 3); PV_W8(); PV_MMA(o[2], A); SBAR();
;   PV_LOAD(A, 4); PV_W8(); PV_MMA(o[3], B); SBAR();
;   PV_LOAD(B, 5); PV_W8(); PV_MMA(o[4], A); SBAR();
;   PV_LOAD(A, 6); PV_W8(); PV_MMA(o[5], B); SBAR();
;   PV_LOAD(B, 7); PV_W8(); PV_MMA(o[6], A); SBAR();
;   PV_W0(); PV_MMA(o[7], B);
; }
.LBB0_113:
	s_setprio 2
	v_add_u32_e32 v160, s8, v226
	ds_read_b64_tr_b16 v[144:145], v160 offset:0
	ds_read_b64_tr_b16 v[146:147], v160 offset:0x800
	ds_read_b64_tr_b16 v[148:149], v160 offset:0x1000
	ds_read_b64_tr_b16 v[150:151], v160 offset:0x1800
	ds_read_b64_tr_b16 v[152:153], v160 offset:0x2000
	ds_read_b64_tr_b16 v[154:155], v160 offset:0x2800
	ds_read_b64_tr_b16 v[156:157], v160 offset:0x3000
	ds_read_b64_tr_b16 v[158:159], v160 offset:0x3800
	ds_read_b64_tr_b16 v[194:195], v160 offset:0x200
	ds_read_b64_tr_b16 v[196:197], v160 offset:0xa00
	ds_read_b64_tr_b16 v[198:199], v160 offset:0x1200
	ds_read_b64_tr_b16 v[200:201], v160 offset:0x1a00
	ds_read_b64_tr_b16 v[202:203], v160 offset:0x2200
	ds_read_b64_tr_b16 v[204:205], v160 offset:0x2a00
	ds_read_b64_tr_b16 v[206:207], v160 offset:0x3200
	ds_read_b64_tr_b16 v[208:209], v160 offset:0x3a00
	s_waitcnt lgkmcnt(8)
	s_nop 0
	v_mfma_f32_32x32x16_bf16 v[96:111], v[128:131], v[144:147], v[96:111]
	v_mfma_f32_32x32x16_bf16 v[96:111], v[132:135], v[148:151], v[96:111]
	v_mfma_f32_32x32x16_bf16 v[96:111], v[136:139], v[152:155], v[96:111]
	v_mfma_f32_32x32x16_bf16 v[96:111], v[140:143], v[156:159], v[96:111]
	ds_read_b64_tr_b16 v[144:145], v160 offset:0x400
	ds_read_b64_tr_b16 v[146:147], v160 offset:0xc00
	ds_read_b64_tr_b16 v[148:149], v160 offset:0x1400
	ds_read_b64_tr_b16 v[150:151], v160 offset:0x1c00
	ds_read_b64_tr_b16 v[152:153], v160 offset:0x2400
	ds_read_b64_tr_b16 v[154:155], v160 offset:0x2c00
	ds_read_b64_tr_b16 v[156:157], v160 offset:0x3400
	ds_read_b64_tr_b16 v[158:159], v160 offset:0x3c00
	s_waitcnt lgkmcnt(8)
	v_mfma_f32_32x32x16_bf16 v[112:127], v[128:131], v[194:197], v[112:127]
	v_mfma_f32_32x32x16_bf16 v[112:127], v[132:135], v[198:201], v[112:127]
	v_mfma_f32_32x32x16_bf16 v[112:127], v[136:139], v[202:205], v[112:127]
	v_mfma_f32_32x32x16_bf16 v[112:127], v[140:143], v[206:209], v[112:127]
	ds_read_b64_tr_b16 v[194:195], v160 offset:0x600
	ds_read_b64_tr_b16 v[196:197], v160 offset:0xe00
	ds_read_b64_tr_b16 v[198:199], v160 offset:0x1600
	ds_read_b64_tr_b16 v[200:201], v160 offset:0x1e00
	ds_read_b64_tr_b16 v[202:203], v160 offset:0x2600
	ds_read_b64_tr_b16 v[204:205], v160 offset:0x2e00
	ds_read_b64_tr_b16 v[206:207], v160 offset:0x3600
	ds_read_b64_tr_b16 v[208:209], v160 offset:0x3e00
	s_waitcnt lgkmcnt(8)
	v_mfma_f32_32x32x16_bf16 v[80:95], v[128:131], v[144:147], v[80:95]
	v_mfma_f32_32x32x16_bf16 v[80:95], v[132:135], v[148:151], v[80:95]
	v_mfma_f32_32x32x16_bf16 v[80:95], v[136:139], v[152:155], v[80:95]
	v_mfma_f32_32x32x16_bf16 v[80:95], v[140:143], v[156:159], v[80:95]
	ds_read_b64_tr_b16 v[144:145], v160 offset:0x4000
	ds_read_b64_tr_b16 v[146:147], v160 offset:0x4800
	ds_read_b64_tr_b16 v[148:149], v160 offset:0x5000
	ds_read_b64_tr_b16 v[150:151], v160 offset:0x5800
	ds_read_b64_tr_b16 v[152:153], v160 offset:0x6000
	ds_read_b64_tr_b16 v[154:155], v160 offset:0x6800
	ds_read_b64_tr_b16 v[156:157], v160 offset:0x7000
	ds_read_b64_tr_b16 v[158:159], v160 offset:0x7800
	s_waitcnt lgkmcnt(8)
	v_mfma_f32_32x32x16_bf16 v[64:79], v[128:131], v[194:197], v[64:79]
	v_mfma_f32_32x32x16_bf16 v[64:79], v[132:135], v[198:201], v[64:79]
	v_mfma_f32_32x32x16_bf16 v[64:79], v[136:139], v[202:205], v[64:79]
	v_mfma_f32_32x32x16_bf16 v[64:79], v[140:143], v[206:209], v[64:79]
	ds_read_b64_tr_b16 v[194:195], v160 offset:0x4200
	ds_read_b64_tr_b16 v[196:197], v160 offset:0x4a00
	ds_read_b64_tr_b16 v[198:199], v160 offset:0x5200
	ds_read_b64_tr_b16 v[200:201], v160 offset:0x5a00
	ds_read_b64_tr_b16 v[202:203], v160 offset:0x6200
	ds_read_b64_tr_b16 v[204:205], v160 offset:0x6a00
	ds_read_b64_tr_b16 v[206:207], v160 offset:0x7200
	ds_read_b64_tr_b16 v[208:209], v160 offset:0x7a00
	s_waitcnt lgkmcnt(8)
	v_mfma_f32_32x32x16_bf16 v[48:63], v[128:131], v[144:147], v[48:63]
	v_mfma_f32_32x32x16_bf16 v[48:63], v[132:135], v[148:151], v[48:63]
	v_mfma_f32_32x32x16_bf16 v[48:63], v[136:139], v[152:155], v[48:63]
	v_mfma_f32_32x32x16_bf16 v[48:63], v[140:143], v[156:159], v[48:63]
	ds_read_b64_tr_b16 v[144:145], v160 offset:0x4400
	ds_read_b64_tr_b16 v[146:147], v160 offset:0x4c00
	ds_read_b64_tr_b16 v[148:149], v160 offset:0x5400
	ds_read_b64_tr_b16 v[150:151], v160 offset:0x5c00
	ds_read_b64_tr_b16 v[152:153], v160 offset:0x6400
	ds_read_b64_tr_b16 v[154:155], v160 offset:0x6c00
	ds_read_b64_tr_b16 v[156:157], v160 offset:0x7400
	ds_read_b64_tr_b16 v[158:159], v160 offset:0x7c00
	s_waitcnt lgkmcnt(8)
	v_mfma_f32_32x32x16_bf16 v[32:47], v[128:131], v[194:197], v[32:47]
	v_mfma_f32_32x32x16_bf16 v[32:47], v[132:135], v[198:201], v[32:47]
	v_mfma_f32_32x32x16_bf16 v[32:47], v[136:139], v[202:205], v[32:47]
	v_mfma_f32_32x32x16_bf16 v[32:47], v[140:143], v[206:209], v[32:47]
	ds_read_b64_tr_b16 v[194:195], v160 offset:0x4600
	ds_read_b64_tr_b16 v[196:197], v160 offset:0x4e00
	ds_read_b64_tr_b16 v[198:199], v160 offset:0x5600
	ds_read_b64_tr_b16 v[200:201], v160 offset:0x5e00
	ds_read_b64_tr_b16 v[202:203], v160 offset:0x6600
	ds_read_b64_tr_b16 v[204:205], v160 offset:0x6e00
	ds_read_b64_tr_b16 v[206:207], v160 offset:0x7600
	ds_read_b64_tr_b16 v[208:209], v160 offset:0x7e00
	s_waitcnt lgkmcnt(8)
	v_mfma_f32_32x32x16_bf16 v[16:31], v[128:131], v[144:147], v[16:31]
	v_mfma_f32_32x32x16_bf16 v[16:31], v[132:135], v[148:151], v[16:31]
	v_mfma_f32_32x32x16_bf16 v[16:31], v[136:139], v[152:155], v[16:31]
	v_mfma_f32_32x32x16_bf16 v[16:31], v[140:143], v[156:159], v[16:31]
	s_waitcnt lgkmcnt(0)
	v_mfma_f32_32x32x16_bf16 v[0:15], v[128:131], v[194:197], v[0:15]
	v_mfma_f32_32x32x16_bf16 v[0:15], v[132:135], v[198:201], v[0:15]
	v_mfma_f32_32x32x16_bf16 v[0:15], v[136:139], v[202:205], v[0:15]
	v_mfma_f32_32x32x16_bf16 v[0:15], v[140:143], v[206:209], v[0:15]
	s_cmpk_lt_u32 s77, 0x113
	s_cbranch_scc1 .LBB0_115
	s_add_i32 s8, s77, 0xffffff67
	s_cmpk_gt_i32 s8, 0xff66
	s_cselect_b32 s8, 0x600, 0
	s_add_i32 s8, s8, 0
	s_add_i32 s8, s8, 0x24800
	v_mov_b32_e32 v128, s8
	ds_read_b32 v160, v128
	s_mov_b64 s[8:9], 0
	s_waitcnt lgkmcnt(0)
	v_mov_b64_e32 v[144:145], v[160:161]
	v_mov_b64_e32 v[146:147], v[162:163]
	v_mov_b64_e32 v[148:149], v[164:165]
	v_mov_b64_e32 v[150:151], v[166:167]
	v_mov_b64_e32 v[152:153], v[168:169]
	v_mov_b64_e32 v[154:155], v[170:171]
	v_mov_b64_e32 v[156:157], v[172:173]
	v_mov_b64_e32 v[158:159], v[174:175]
	s_branch .LBB0_116

; __device__ __forceinline__ void partialSM(f32x16& p0, f32x16& p1, float& m_reg, float& mn, float& alpha) {
;   constexpr float C = LOG2E;
;   float pmax = p0[0];
; #pragma unroll
;   for (int r = 1; r < 16; ++r) pmax = fmaxf(pmax, p0[r]);
; #pragma unroll
;   for (int r = 0; r < 16; ++r) pmax = fmaxf(pmax, p1[r]);
;   { auto rr = __builtin_amdgcn_permlane32_swap(__float_as_uint(pmax), __float_as_uint(pmax), false, false);
;     pmax = fmaxf(__uint_as_float(rr[0]), __uint_as_float(rr[1])); }
;   if (__builtin_expect(__all(pmax - m_reg <= THR), 1)) { mn = m_reg; alpha = 1.f; }
;   else { mn = fmaxf(m_reg, pmax); alpha = __builtin_amdgcn_exp2f((m_reg - mn) * C); m_reg = mn; }
; __device__ __forceinline__ void qkt(f32x16& p0, f32x16& p1, const char* Ks, const bf16x8* qr, int r32, int hi, const LAS float* tab, int rel0, int farmode) {
;     ...
;   for (int d0 = 0; d0 < 8; ++d0) { int cb = (d0 * 16 + hi * 8) * 2;
;     bf16x8 b0 = *reinterpret_cast<const bf16x8*>(Ks + KSWZ(r32, cb));
;     bf16x8 b1 = *reinterpret_cast<const bf16x8*>(Ks + KSWZ(32 + r32, cb));
;     p0 = __builtin_amdgcn_mfma_f32_32x32x16_bf16(b0, qr[d0], p0, 0, 0, 0);
;     p1 = __builtin_amdgcn_mfma_f32_32x32x16_bf16(b1, qr[d0], p1, 0, 0, 0); }
.LBB0_118:
	s_add_i32 s8, s1, 0
	v_mov_b32_e32 v145, v160
	v_add3_u32 v160, s8, v236, v235
	ds_read_b128 v[194:197], v160
	ds_read_b128 v[198:201], v160 offset:8192
	v_add3_u32 v160, s8, v237, v235
	ds_read_b128 v[202:205], v160
	ds_read_b128 v[206:209], v160 offset:8192
	v_add3_u32 v160, s8, v238, v235
	s_waitcnt lgkmcnt(3)
	v_mfma_f32_32x32x16_bf16 v[144:159], v[194:197], v[162:165], v[144:159]
	ds_read_b128 v[194:197], v160
	s_waitcnt lgkmcnt(3)
	v_mfma_f32_32x32x16_bf16 v[128:143], v[198:201], v[162:165], v[128:143]
	ds_read_b128 v[198:201], v160 offset:8192
	v_add3_u32 v160, s8, v239, v235
	s_waitcnt lgkmcnt(3)
	v_mfma_f32_32x32x16_bf16 v[144:159], v[202:205], v[166:169], v[144:159]
	ds_read_b128 v[202:205], v160
	s_waitcnt lgkmcnt(3)
	v_mfma_f32_32x32x16_bf16 v[128:143], v[206:209], v[166:169], v[128:143]
	ds_read_b128 v[206:209], v160 offset:8192
	v_add3_u32 v160, s8, v240, v235
	s_waitcnt lgkmcnt(3)
	v_mfma_f32_32x32x16_bf16 v[144:159], v[194:197], v[170:173], v[144:159]
	ds_read_b128 v[194:197], v160
	s_waitcnt lgkmcnt(3)
	v_mfma_f32_32x32x16_bf16 v[128:143], v[198:201], v[170:173], v[128:143]
	ds_read_b128 v[198:201], v160 offset:8192
	v_add3_u32 v160, s8, v241, v235
	s_waitcnt lgkmcnt(3)
	v_mfma_f32_32x32x16_bf16 v[144:159], v[202:205], v[174:177], v[144:159]
	ds_read_b128 v[202:205], v160
	s_waitcnt lgkmcnt(3)
	v_mfma_f32_32x32x16_bf16 v[128:143], v[206:209], v[174:177], v[128:143]
	ds_read_b128 v[206:209], v160 offset:8192
	v_add3_u32 v160, s8, v242, v235
	s_waitcnt lgkmcnt(3)
	v_mfma_f32_32x32x16_bf16 v[144:159], v[194:197], v[178:181], v[144:159]
	ds_read_b128 v[194:197], v160
	s_waitcnt lgkmcnt(3)
	v_mfma_f32_32x32x16_bf16 v[128:143], v[198:201], v[178:181], v[128:143]
	ds_read_b128 v[198:201], v160 offset:8192
	v_add3_u32 v160, s8, v243, v235
	s_waitcnt lgkmcnt(3)
	v_mfma_f32_32x32x16_bf16 v[144:159], v[202:205], v[182:185], v[144:159]
	ds_read_b128 v[202:205], v160
	s_waitcnt lgkmcnt(3)
	v_mfma_f32_32x32x16_bf16 v[128:143], v[206:209], v[182:185], v[128:143]
	ds_read_b128 v[206:209], v160 offset:8192
	s_waitcnt lgkmcnt(3)
	v_mfma_f32_32x32x16_bf16 v[144:159], v[194:197], v[186:189], v[144:159]
	s_waitcnt lgkmcnt(2)
	v_mfma_f32_32x32x16_bf16 v[128:143], v[198:201], v[186:189], v[128:143]
	s_waitcnt lgkmcnt(1)
	v_mfma_f32_32x32x16_bf16 v[144:159], v[202:205], v[190:193], v[144:159]
	s_waitcnt lgkmcnt(0)
	v_mfma_f32_32x32x16_bf16 v[128:143], v[206:209], v[190:193], v[128:143]
	s_setprio 0
	s_nop 9
	v_max_f32_e32 v160, v145, v145
	v_max_f32_e32 v194, v144, v144
	v_max_f32_e32 v160, v194, v160
	v_max3_f32 v160, v160, v146, v147
	v_max3_f32 v160, v160, v148, v149
	v_max3_f32 v160, v160, v150, v151
	v_max3_f32 v160, v160, v152, v153
	v_max3_f32 v160, v160, v154, v155
	v_max3_f32 v160, v160, v156, v157
	v_max3_f32 v160, v160, v158, v159
	v_max3_f32 v160, v160, v128, v129
	v_max3_f32 v160, v160, v130, v131
	v_max3_f32 v160, v160, v132, v133
	v_max3_f32 v160, v160, v134, v135
	v_max3_f32 v160, v160, v136, v137
	v_max3_f32 v160, v160, v138, v139
	v_max3_f32 v160, v160, v140, v141
	v_max3_f32 v160, v160, v142, v143
	v_mov_b32_e32 v194, v160
	s_nop 1
	v_permlane32_swap_b32_e32 v160, v194
	v_max_f32_e32 v194, v194, v194
	v_max_f32_e32 v160, v160, v160
	v_max_f32_e32 v160, v160, v194
	v_sub_f32_e32 v194, v160, v250
	v_cmp_ge_f32_e32 vcc, s53, v194
	v_max_f32_e32 v194, v250, v250
	v_max_f32_e32 v253, v194, v160
	v_sub_f32_e32 v160, v250, v253
	v_mul_f32_e32 v160, 0x3fb8aa3b, v160
	v_exp_f32_e32 v160, v160
	s_cmp_eq_u64 vcc, exec
	s_cselect_b64 s[8:9], -1, 0
	v_cndmask_b32_e64 v160, v160, 1.0, s[8:9]
	v_cmp_gt_f32_e32 vcc, 1.0, v160
	s_cbranch_vccz .LBB0_122
	s_and_saveexec_b64 s[10:11], s[6:7]
	v_lshl_add_u32 v194, v213, 2, s80
	ds_write_b32 v194, v160 offset:128
	s_or_b64 exec, exec, s[10:11]
	s_waitcnt lgkmcnt(0)
	v_add_u32_e32 v194, s80, v234
	ds_read_b128 v[206:209], v194 offset:224
	ds_read_b128 v[202:205], v194 offset:192
	ds_read_b128 v[198:201], v194 offset:160
	ds_read_b128 v[194:197], v194 offset:128
	s_waitcnt lgkmcnt(0)
	v_pk_mul_f32 v[108:109], v[108:109], v[206:207]
	v_pk_mul_f32 v[104:105], v[104:105], v[202:203]
	v_pk_mul_f32 v[100:101], v[100:101], v[198:199]
	v_pk_mul_f32 v[110:111], v[110:111], v[208:209]
	v_pk_mul_f32 v[106:107], v[106:107], v[204:205]
	v_pk_mul_f32 v[102:103], v[102:103], v[200:201]
	v_pk_mul_f32 v[98:99], v[98:99], v[196:197]
	v_pk_mul_f32 v[96:97], v[96:97], v[194:195]
	v_pk_mul_f32 v[124:125], v[124:125], v[206:207]
	v_pk_mul_f32 v[120:121], v[120:121], v[202:203]
	v_pk_mul_f32 v[116:117], v[116:117], v[198:199]
	v_pk_mul_f32 v[126:127], v[126:127], v[208:209]
	v_pk_mul_f32 v[122:123], v[122:123], v[204:205]
	v_pk_mul_f32 v[118:119], v[118:119], v[200:201]
	v_pk_mul_f32 v[114:115], v[114:115], v[196:197]
	v_pk_mul_f32 v[112:113], v[112:113], v[194:195]
	v_pk_mul_f32 v[92:93], v[92:93], v[206:207]
	v_pk_mul_f32 v[88:89], v[88:89], v[202:203]
	v_pk_mul_f32 v[84:85], v[84:85], v[198:199]
	v_pk_mul_f32 v[94:95], v[94:95], v[208:209]
	v_pk_mul_f32 v[90:91], v[90:91], v[204:205]
	v_pk_mul_f32 v[86:87], v[86:87], v[200:201]
	v_pk_mul_f32 v[82:83], v[82:83], v[196:197]
	v_pk_mul_f32 v[80:81], v[80:81], v[194:195]
	v_pk_mul_f32 v[76:77], v[76:77], v[206:207]
	v_pk_mul_f32 v[72:73], v[72:73], v[202:203]
	v_pk_mul_f32 v[68:69], v[68:69], v[198:199]
	v_pk_mul_f32 v[78:79], v[78:79], v[208:209]
	v_pk_mul_f32 v[74:75], v[74:75], v[204:205]
	v_pk_mul_f32 v[70:71], v[70:71], v[200:201]
	v_pk_mul_f32 v[66:67], v[66:67], v[196:197]
	v_pk_mul_f32 v[64:65], v[64:65], v[194:195]
	v_pk_mul_f32 v[60:61], v[60:61], v[206:207]
	v_pk_mul_f32 v[56:57], v[56:57], v[202:203]
	v_pk_mul_f32 v[52:53], v[52:53], v[198:199]
	v_pk_mul_f32 v[62:63], v[62:63], v[208:209]
	v_pk_mul_f32 v[58:59], v[58:59], v[204:205]
	v_pk_mul_f32 v[54:55], v[54:55], v[200:201]
	v_pk_mul_f32 v[50:51], v[50:51], v[196:197]
	v_pk_mul_f32 v[48:49], v[48:49], v[194:195]
	v_pk_mul_f32 v[44:45], v[44:45], v[206:207]
	v_pk_mul_f32 v[40:41], v[40:41], v[202:203]
	v_pk_mul_f32 v[36:37], v[36:37], v[198:199]
	v_pk_mul_f32 v[46:47], v[46:47], v[208:209]
	v_pk_mul_f32 v[42:43], v[42:43], v[204:205]
	v_pk_mul_f32 v[38:39], v[38:39], v[200:201]
	v_pk_mul_f32 v[34:35], v[34:35], v[196:197]
	v_pk_mul_f32 v[32:33], v[32:33], v[194:195]
	v_pk_mul_f32 v[28:29], v[28:29], v[206:207]
	v_pk_mul_f32 v[24:25], v[24:25], v[202:203]
	v_pk_mul_f32 v[20:21], v[20:21], v[198:199]
	v_pk_mul_f32 v[30:31], v[30:31], v[208:209]
	v_pk_mul_f32 v[26:27], v[26:27], v[204:205]
	v_pk_mul_f32 v[22:23], v[22:23], v[200:201]
	v_pk_mul_f32 v[18:19], v[18:19], v[196:197]
	v_pk_mul_f32 v[16:17], v[16:17], v[194:195]
	v_pk_mul_f32 v[12:13], v[12:13], v[206:207]
	v_pk_mul_f32 v[8:9], v[8:9], v[202:203]
	v_pk_mul_f32 v[4:5], v[4:5], v[198:199]
	v_pk_mul_f32 v[14:15], v[14:15], v[208:209]
	v_pk_mul_f32 v[10:11], v[10:11], v[204:205]
	v_pk_mul_f32 v[6:7], v[6:7], v[200:201]
	v_pk_mul_f32 v[2:3], v[2:3], v[196:197]
	v_pk_mul_f32 v[0:1], v[0:1], v[194:195]

; __device__ __forceinline__ void partialSM(f32x16& p0, f32x16& p1, float& m_reg, float& mn, float& alpha) {
;   constexpr float C = LOG2E;
;   float pmax = p0[0];
; #pragma unroll
;   for (int r = 1; r < 16; ++r) pmax = fmaxf(pmax, p0[r]);
; #pragma unroll
;   for (int r = 0; r < 16; ++r) pmax = fmaxf(pmax, p1[r]);
;   { auto rr = __builtin_amdgcn_permlane32_swap(__float_as_uint(pmax), __float_as_uint(pmax), false, false);
;     pmax = fmaxf(__uint_as_float(rr[0]), __uint_as_float(rr[1])); }
;   if (__builtin_expect(__all(pmax - m_reg <= THR), 1)) { mn = m_reg; alpha = 1.f; }
;   else { mn = fmaxf(m_reg, pmax); alpha = __builtin_amdgcn_exp2f((m_reg - mn) * C); m_reg = mn; }
; __device__ __forceinline__ void qkt(f32x16& p0, f32x16& p1, const char* Ks, const bf16x8* qr, int r32, int hi, const LAS float* tab, int rel0, int farmode) {
;     ...
;   for (int d0 = 0; d0 < 8; ++d0) { int cb = (d0 * 16 + hi * 8) * 2;
;     bf16x8 b0 = *reinterpret_cast<const bf16x8*>(Ks + KSWZ(r32, cb));
;     bf16x8 b1 = *reinterpret_cast<const bf16x8*>(Ks + KSWZ(32 + r32, cb));
;     p0 = __builtin_amdgcn_mfma_f32_32x32x16_bf16(b0, qr[d0], p0, 0, 0, 0);
;     p1 = __builtin_amdgcn_mfma_f32_32x32x16_bf16(b1, qr[d0], p1, 0, 0, 0); }
.LBB0_133:
	s_add_i32 s8, s24, 0
	v_mov_b32_e32 v145, v160
	v_add3_u32 v160, s8, v236, v235
	ds_read_b128 v[194:197], v160
	ds_read_b128 v[198:201], v160 offset:8192
	v_add3_u32 v160, s8, v237, v235
	ds_read_b128 v[202:205], v160
	ds_read_b128 v[206:209], v160 offset:8192
	v_add3_u32 v160, s8, v238, v235
	s_waitcnt lgkmcnt(3)
	v_mfma_f32_32x32x16_bf16 v[144:159], v[194:197], v[162:165], v[144:159]
	ds_read_b128 v[194:197], v160
	s_waitcnt lgkmcnt(3)
	v_mfma_f32_32x32x16_bf16 v[128:143], v[198:201], v[162:165], v[128:143]
	ds_read_b128 v[198:201], v160 offset:8192
	v_add3_u32 v160, s8, v239, v235
	s_waitcnt lgkmcnt(3)
	v_mfma_f32_32x32x16_bf16 v[144:159], v[202:205], v[166:169], v[144:159]
	ds_read_b128 v[202:205], v160
	s_waitcnt lgkmcnt(3)
	v_mfma_f32_32x32x16_bf16 v[128:143], v[206:209], v[166:169], v[128:143]
	ds_read_b128 v[206:209], v160 offset:8192
	v_add3_u32 v160, s8, v240, v235
	s_waitcnt lgkmcnt(3)
	v_mfma_f32_32x32x16_bf16 v[144:159], v[194:197], v[170:173], v[144:159]
	ds_read_b128 v[194:197], v160
	s_waitcnt lgkmcnt(3)
	v_mfma_f32_32x32x16_bf16 v[128:143], v[198:201], v[170:173], v[128:143]
	ds_read_b128 v[198:201], v160 offset:8192
	v_add3_u32 v160, s8, v241, v235
	s_waitcnt lgkmcnt(3)
	v_mfma_f32_32x32x16_bf16 v[144:159], v[202:205], v[174:177], v[144:159]
	ds_read_b128 v[202:205], v160
	s_waitcnt lgkmcnt(3)
	v_mfma_f32_32x32x16_bf16 v[128:143], v[206:209], v[174:177], v[128:143]
	ds_read_b128 v[206:209], v160 offset:8192
	v_add3_u32 v160, s8, v242, v235
	s_waitcnt lgkmcnt(3)
	v_mfma_f32_32x32x16_bf16 v[144:159], v[194:197], v[178:181], v[144:159]
	ds_read_b128 v[194:197], v160
	s_waitcnt lgkmcnt(3)
	v_mfma_f32_32x32x16_bf16 v[128:143], v[198:201], v[178:181], v[128:143]
	ds_read_b128 v[198:201], v160 offset:8192
	v_add3_u32 v160, s8, v243, v235
	s_waitcnt lgkmcnt(3)
	v_mfma_f32_32x32x16_bf16 v[144:159], v[202:205], v[182:185], v[144:159]
	ds_read_b128 v[202:205], v160
	s_waitcnt lgkmcnt(3)
	v_mfma_f32_32x32x16_bf16 v[128:143], v[206:209], v[182:185], v[128:143]
	ds_read_b128 v[206:209], v160 offset:8192
	s_waitcnt lgkmcnt(3)
	v_mfma_f32_32x32x16_bf16 v[144:159], v[194:197], v[186:189], v[144:159]
	s_waitcnt lgkmcnt(2)
	v_mfma_f32_32x32x16_bf16 v[128:143], v[198:201], v[186:189], v[128:143]
	s_waitcnt lgkmcnt(1)
	v_mfma_f32_32x32x16_bf16 v[144:159], v[202:205], v[190:193], v[144:159]
	s_waitcnt lgkmcnt(0)
	v_mfma_f32_32x32x16_bf16 v[128:143], v[206:209], v[190:193], v[128:143]
	s_setprio 0
	s_nop 9
	v_max_f32_e32 v160, v145, v145
	v_max_f32_e32 v194, v144, v144
	v_max_f32_e32 v160, v194, v160
	v_max3_f32 v160, v160, v146, v147
	v_max3_f32 v160, v160, v148, v149
	v_max3_f32 v160, v160, v150, v151
	v_max3_f32 v160, v160, v152, v153
	v_max3_f32 v160, v160, v154, v155
	v_max3_f32 v160, v160, v156, v157
	v_max3_f32 v160, v160, v158, v159
	v_max3_f32 v160, v160, v128, v129
	v_max3_f32 v160, v160, v130, v131
	v_max3_f32 v160, v160, v132, v133
	v_max3_f32 v160, v160, v134, v135
	v_max3_f32 v160, v160, v136, v137
	v_max3_f32 v160, v160, v138, v139
	v_max3_f32 v160, v160, v140, v141
	v_max3_f32 v160, v160, v142, v143
	v_mov_b32_e32 v194, v160
	s_nop 1
	v_permlane32_swap_b32_e32 v160, v194
	v_max_f32_e32 v194, v194, v194
	v_max_f32_e32 v160, v160, v160
	v_max_f32_e32 v160, v160, v194
	v_sub_f32_e32 v194, v160, v227
	v_cmp_ge_f32_e32 vcc, s53, v194
	v_max_f32_e32 v194, v227, v227
	v_max_f32_e32 v229, v194, v160
	v_sub_f32_e32 v160, v227, v229
	v_mul_f32_e32 v160, 0x3fb8aa3b, v160
	v_exp_f32_e32 v160, v160
	s_cmp_eq_u64 vcc, exec
	s_cselect_b64 s[8:9], -1, 0
	v_cndmask_b32_e64 v160, v160, 1.0, s[8:9]
	v_cmp_gt_f32_e32 vcc, 1.0, v160
	s_cbranch_vccz .LBB0_137
	s_and_saveexec_b64 s[10:11], s[6:7]
	ds_write_b32 v234, v160 offset:128
	s_or_b64 exec, exec, s[10:11]
	s_waitcnt lgkmcnt(0)
	v_add_u32_e32 v194, s80, v216
	ds_read_b128 v[206:209], v194 offset:224
	ds_read_b128 v[202:205], v194 offset:192
	ds_read_b128 v[198:201], v194 offset:160
	ds_read_b128 v[194:197], v194 offset:128
	s_waitcnt lgkmcnt(3)
	v_pk_mul_f32 v[108:109], v[108:109], v[206:207]
	s_waitcnt lgkmcnt(2)
	v_pk_mul_f32 v[104:105], v[104:105], v[202:203]
	s_waitcnt lgkmcnt(1)
	v_pk_mul_f32 v[100:101], v[100:101], v[198:199]
	v_pk_mul_f32 v[110:111], v[110:111], v[208:209]
	v_pk_mul_f32 v[106:107], v[106:107], v[204:205]
	v_pk_mul_f32 v[102:103], v[102:103], v[200:201]
	s_waitcnt lgkmcnt(0)
	v_pk_mul_f32 v[98:99], v[98:99], v[196:197]
	v_pk_mul_f32 v[96:97], v[96:97], v[194:195]
	v_pk_mul_f32 v[124:125], v[124:125], v[206:207]
	v_pk_mul_f32 v[120:121], v[120:121], v[202:203]
	v_pk_mul_f32 v[116:117], v[116:117], v[198:199]
	v_pk_mul_f32 v[126:127], v[126:127], v[208:209]
	v_pk_mul_f32 v[122:123], v[122:123], v[204:205]
	v_pk_mul_f32 v[118:119], v[118:119], v[200:201]
	v_pk_mul_f32 v[114:115], v[114:115], v[196:197]
	v_pk_mul_f32 v[112:113], v[112:113], v[194:195]
	v_pk_mul_f32 v[92:93], v[92:93], v[206:207]
	v_pk_mul_f32 v[88:89], v[88:89], v[202:203]
	v_pk_mul_f32 v[84:85], v[84:85], v[198:199]
	v_pk_mul_f32 v[94:95], v[94:95], v[208:209]
	v_pk_mul_f32 v[90:91], v[90:91], v[204:205]
	v_pk_mul_f32 v[86:87], v[86:87], v[200:201]
	v_pk_mul_f32 v[82:83], v[82:83], v[196:197]
	v_pk_mul_f32 v[80:81], v[80:81], v[194:195]
	v_pk_mul_f32 v[76:77], v[76:77], v[206:207]
	v_pk_mul_f32 v[72:73], v[72:73], v[202:203]
	v_pk_mul_f32 v[68:69], v[68:69], v[198:199]
	v_pk_mul_f32 v[78:79], v[78:79], v[208:209]
	v_pk_mul_f32 v[74:75], v[74:75], v[204:205]
	v_pk_mul_f32 v[70:71], v[70:71], v[200:201]
	v_pk_mul_f32 v[66:67], v[66:67], v[196:197]
	v_pk_mul_f32 v[64:65], v[64:65], v[194:195]
	v_pk_mul_f32 v[60:61], v[60:61], v[206:207]
	v_pk_mul_f32 v[56:57], v[56:57], v[202:203]
	v_pk_mul_f32 v[52:53], v[52:53], v[198:199]
	v_pk_mul_f32 v[62:63], v[62:63], v[208:209]
	v_pk_mul_f32 v[58:59], v[58:59], v[204:205]
	v_pk_mul_f32 v[54:55], v[54:55], v[200:201]
	v_pk_mul_f32 v[50:51], v[50:51], v[196:197]
	v_pk_mul_f32 v[48:49], v[48:49], v[194:195]
	v_pk_mul_f32 v[44:45], v[44:45], v[206:207]
	v_pk_mul_f32 v[40:41], v[40:41], v[202:203]
	v_pk_mul_f32 v[36:37], v[36:37], v[198:199]
	v_pk_mul_f32 v[46:47], v[46:47], v[208:209]
	v_pk_mul_f32 v[42:43], v[42:43], v[204:205]
	v_pk_mul_f32 v[38:39], v[38:39], v[200:201]
	v_pk_mul_f32 v[34:35], v[34:35], v[196:197]
	v_pk_mul_f32 v[32:33], v[32:33], v[194:195]
	v_pk_mul_f32 v[28:29], v[28:29], v[206:207]
	v_pk_mul_f32 v[24:25], v[24:25], v[202:203]
	v_pk_mul_f32 v[20:21], v[20:21], v[198:199]
	v_pk_mul_f32 v[30:31], v[30:31], v[208:209]
	v_pk_mul_f32 v[26:27], v[26:27], v[204:205]
	v_pk_mul_f32 v[22:23], v[22:23], v[200:201]
	v_pk_mul_f32 v[18:19], v[18:19], v[196:197]
	v_pk_mul_f32 v[16:17], v[16:17], v[194:195]
	v_pk_mul_f32 v[12:13], v[12:13], v[206:207]
	v_pk_mul_f32 v[8:9], v[8:9], v[202:203]
	v_pk_mul_f32 v[4:5], v[4:5], v[198:199]
	v_pk_mul_f32 v[14:15], v[14:15], v[208:209]
	v_pk_mul_f32 v[10:11], v[10:11], v[204:205]
	v_pk_mul_f32 v[6:7], v[6:7], v[200:201]
	v_pk_mul_f32 v[2:3], v[2:3], v[196:197]
	v_pk_mul_f32 v[0:1], v[0:1], v[194:195]
